# GEMM epilogues ph6+ph8: lanes l / l^16 exchange bf16 fragments via v_permlane16_swap, one 16-byte store per 8 columns (was two 8-byte stores)
# speedup vs baseline: 1.0182x; 1.0122x over previous
.LBB0_1662:
	ds_read_b128 v[144:147], v156
	ds_read_b128 v[148:151], v156 offset:1024
	ds_read_b128 v[160:163], v156 offset:2048
	ds_read_b128 v[164:167], v156 offset:3072
	s_add_u32 s26, s24, 0xfff80080
	s_addc_u32 s27, s25, -1
	s_cmp_eq_u32 s56, 28
	s_cselect_b32 s29, s3, s27
	s_cselect_b32 s28, s17, s26
	s_cselect_b32 s27, s15, s55
	s_cselect_b32 s26, s53, s54
	v_lshl_add_u64 v[184:185], s[24:25], 0, v[136:137]
	s_add_i32 m0, s23, 0xc000
	ds_read_b128 v[168:171], v157
	ds_read_b128 v[172:175], v157 offset:1024
	ds_read_b128 v[176:179], v157 offset:2048
	ds_read_b128 v[180:183], v157 offset:3072
	ds_read_b128 v[188:191], v157 offset:4096
	ds_read_b128 v[192:195], v157 offset:5120
	ds_read_b128 v[196:199], v157 offset:6144
	ds_read_b128 v[200:203], v157 offset:7168
	global_load_lds_dwordx4 v[184:185], off
	v_lshl_add_u64 v[184:185], s[24:25], 0, v[138:139]
	s_add_i32 m0, s23, 0xe000
	s_nop 0
	global_load_lds_dwordx4 v[184:185], off
	s_waitcnt lgkmcnt(8)
	s_barrier
	s_waitcnt lgkmcnt(0)
	s_setprio 1
	s_waitcnt lgkmcnt(0)
	v_mfma_f32_16x16x32_bf16 v[126:129], v[144:147], v[168:171], v[126:129]
	v_mfma_f32_16x16x32_bf16 v[122:125], v[160:163], v[168:171], v[122:125]
	v_mfma_f32_16x16x32_bf16 v[110:113], v[144:147], v[176:179], v[110:113]
	v_mfma_f32_16x16x32_bf16 v[106:109], v[160:163], v[176:179], v[106:109]
	v_mfma_f32_16x16x32_bf16 v[94:97], v[144:147], v[188:191], v[94:97]
	v_mfma_f32_16x16x32_bf16 v[90:93], v[160:163], v[188:191], v[90:93]
	v_mfma_f32_16x16x32_bf16 v[78:81], v[144:147], v[196:199], v[78:81]
	v_mfma_f32_16x16x32_bf16 v[74:77], v[160:163], v[196:199], v[74:77]
	v_mfma_f32_16x16x32_bf16 v[126:129], v[148:151], v[172:175], v[126:129]
	v_mfma_f32_16x16x32_bf16 v[122:125], v[164:167], v[172:175], v[122:125]
	v_mfma_f32_16x16x32_bf16 v[110:113], v[148:151], v[180:183], v[110:113]
	v_mfma_f32_16x16x32_bf16 v[106:109], v[164:167], v[180:183], v[106:109]
	v_mfma_f32_16x16x32_bf16 v[94:97], v[148:151], v[192:195], v[94:97]
	v_mfma_f32_16x16x32_bf16 v[90:93], v[164:167], v[192:195], v[90:93]
	v_mfma_f32_16x16x32_bf16 v[78:81], v[148:151], v[200:203], v[78:81]
	v_mfma_f32_16x16x32_bf16 v[74:77], v[164:167], v[200:203], v[74:77]
	s_setprio 0
	s_barrier
	s_add_i32 s57, s49, s37
	v_lshl_add_u64 v[184:185], s[26:27], 0, v[130:131]
	s_mov_b32 m0, s57
	ds_read_b128 v[204:207], v158
	ds_read_b128 v[208:211], v158 offset:1024
	ds_read_b128 v[212:215], v158 offset:2048
	ds_read_b128 v[216:219], v158 offset:3072
	global_load_lds_dwordx4 v[184:185], off
	v_lshl_add_u64 v[220:221], s[26:27], 0, v[132:133]
	s_add_i32 m0, s57, 0x2000
	s_nop 0
	global_load_lds_dwordx4 v[220:221], off
	s_barrier
	s_waitcnt lgkmcnt(0)
	s_setprio 1
	s_waitcnt lgkmcnt(0)
	v_mfma_f32_16x16x32_bf16 v[118:121], v[204:207], v[168:171], v[118:121]
	v_mfma_f32_16x16x32_bf16 v[114:117], v[212:215], v[168:171], v[114:117]
	v_mfma_f32_16x16x32_bf16 v[102:105], v[204:207], v[176:179], v[102:105]
	v_mfma_f32_16x16x32_bf16 v[98:101], v[212:215], v[176:179], v[98:101]
	v_mfma_f32_16x16x32_bf16 v[86:89], v[204:207], v[188:191], v[86:89]
	v_mfma_f32_16x16x32_bf16 v[82:85], v[212:215], v[188:191], v[82:85]
	v_mfma_f32_16x16x32_bf16 v[70:73], v[204:207], v[196:199], v[70:73]
	v_mfma_f32_16x16x32_bf16 v[66:69], v[212:215], v[196:199], v[66:69]
	v_mfma_f32_16x16x32_bf16 v[118:121], v[208:211], v[172:175], v[118:121]
	v_mfma_f32_16x16x32_bf16 v[114:117], v[216:219], v[172:175], v[114:117]
	v_mfma_f32_16x16x32_bf16 v[102:105], v[208:211], v[180:183], v[102:105]
	v_mfma_f32_16x16x32_bf16 v[98:101], v[216:219], v[180:183], v[98:101]
	v_mfma_f32_16x16x32_bf16 v[86:89], v[208:211], v[192:195], v[86:89]
	v_mfma_f32_16x16x32_bf16 v[82:85], v[216:219], v[192:195], v[82:85]
	v_mfma_f32_16x16x32_bf16 v[70:73], v[208:211], v[200:203], v[70:73]
	v_mfma_f32_16x16x32_bf16 v[66:69], v[216:219], v[200:203], v[66:69]
	s_setprio 0
	s_mov_b32 m0, s23
	v_lshl_add_u64 v[222:223], s[28:29], 0, v[130:131]
	s_barrier
	ds_read_b128 v[168:171], v157 offset:16384
	ds_read_b128 v[172:175], v157 offset:17408
	ds_read_b128 v[176:179], v157 offset:18432
	ds_read_b128 v[180:183], v157 offset:19456
	ds_read_b128 v[188:191], v157 offset:20480
	ds_read_b128 v[192:195], v157 offset:21504
	ds_read_b128 v[196:199], v157 offset:22528
	ds_read_b128 v[200:203], v157 offset:23552
	global_load_lds_dwordx4 v[222:223], off
	v_lshl_add_u64 v[224:225], s[28:29], 0, v[132:133]
	s_mov_b32 m0, s38
	s_nop 0
	global_load_lds_dwordx4 v[224:225], off
	s_barrier
	s_waitcnt lgkmcnt(0)
	s_setprio 1
	s_waitcnt lgkmcnt(0)
	v_mfma_f32_16x16x32_bf16 v[62:65], v[144:147], v[168:171], v[62:65]
	v_mfma_f32_16x16x32_bf16 v[58:61], v[160:163], v[168:171], v[58:61]
	v_mfma_f32_16x16x32_bf16 v[46:49], v[144:147], v[176:179], v[46:49]
	v_mfma_f32_16x16x32_bf16 v[42:45], v[160:163], v[176:179], v[42:45]
	v_mfma_f32_16x16x32_bf16 v[30:33], v[144:147], v[188:191], v[30:33]
	v_mfma_f32_16x16x32_bf16 v[26:29], v[160:163], v[188:191], v[26:29]
	v_mfma_f32_16x16x32_bf16 v[14:17], v[144:147], v[196:199], v[14:17]
	v_mfma_f32_16x16x32_bf16 v[10:13], v[160:163], v[196:199], v[10:13]
	v_mfma_f32_16x16x32_bf16 v[62:65], v[148:151], v[172:175], v[62:65]
	v_mfma_f32_16x16x32_bf16 v[58:61], v[164:167], v[172:175], v[58:61]
	v_mfma_f32_16x16x32_bf16 v[46:49], v[148:151], v[180:183], v[46:49]
	v_mfma_f32_16x16x32_bf16 v[42:45], v[164:167], v[180:183], v[42:45]
	v_mfma_f32_16x16x32_bf16 v[30:33], v[148:151], v[192:195], v[30:33]
	v_mfma_f32_16x16x32_bf16 v[26:29], v[164:167], v[192:195], v[26:29]
	v_mfma_f32_16x16x32_bf16 v[14:17], v[148:151], v[200:203], v[14:17]
	v_mfma_f32_16x16x32_bf16 v[10:13], v[164:167], v[200:203], v[10:13]
	s_setprio 0
	s_barrier
	s_add_u32 s58, s26, 0x80000
	s_addc_u32 s59, s27, 0
	s_add_i32 s57, s51, s37
	v_lshl_add_u64 v[144:145], s[58:59], 0, v[130:131]
	s_mov_b32 m0, s57
	s_nop 0
	global_load_lds_dwordx4 v[144:145], off
	v_lshl_add_u64 v[144:145], s[58:59], 0, v[132:133]
	s_add_i32 m0, s57, 0x2000
	s_nop 0
	global_load_lds_dwordx4 v[144:145], off
	s_waitcnt vmcnt(6)
	s_barrier
	s_setprio 1
	v_mfma_f32_16x16x32_bf16 v[54:57], v[204:207], v[168:171], v[54:57]
	v_mfma_f32_16x16x32_bf16 v[50:53], v[212:215], v[168:171], v[50:53]
	v_mfma_f32_16x16x32_bf16 v[38:41], v[204:207], v[176:179], v[38:41]
	v_mfma_f32_16x16x32_bf16 v[34:37], v[212:215], v[176:179], v[34:37]
	v_mfma_f32_16x16x32_bf16 v[22:25], v[204:207], v[188:191], v[22:25]
	v_mfma_f32_16x16x32_bf16 v[18:21], v[212:215], v[188:191], v[18:21]
	v_mfma_f32_16x16x32_bf16 v[6:9], v[204:207], v[196:199], v[6:9]
	v_mfma_f32_16x16x32_bf16 v[2:5], v[212:215], v[196:199], v[2:5]
	v_mfma_f32_16x16x32_bf16 v[54:57], v[208:211], v[172:175], v[54:57]
	v_mfma_f32_16x16x32_bf16 v[50:53], v[216:219], v[172:175], v[50:53]
	v_mfma_f32_16x16x32_bf16 v[38:41], v[208:211], v[180:183], v[38:41]
	v_mfma_f32_16x16x32_bf16 v[34:37], v[216:219], v[180:183], v[34:37]
	v_mfma_f32_16x16x32_bf16 v[22:25], v[208:211], v[192:195], v[22:25]
	v_mfma_f32_16x16x32_bf16 v[18:21], v[216:219], v[192:195], v[18:21]
	v_mfma_f32_16x16x32_bf16 v[6:9], v[208:211], v[200:203], v[6:9]
	v_mfma_f32_16x16x32_bf16 v[2:5], v[216:219], v[200:203], v[2:5]
	s_setprio 0
	s_add_i32 s57, 0, 0x18000
	v_add_u32_e32 v134, s57, v154
	s_barrier
	ds_read_b128 v[144:147], v134
	ds_read_b128 v[148:151], v134 offset:1024
	ds_read_b128 v[160:163], v134 offset:2048
	ds_read_b128 v[164:167], v134 offset:3072
	s_add_u32 s28, s28, 0x80000
	s_addc_u32 s29, s29, 0
	s_mov_b32 m0, s39
	v_lshl_add_u64 v[204:205], s[28:29], 0, v[130:131]
	ds_read_b128 v[168:171], v157 offset:32768
	ds_read_b128 v[172:175], v157 offset:33792
	ds_read_b128 v[176:179], v157 offset:34816
	ds_read_b128 v[180:183], v157 offset:35840
	ds_read_b128 v[188:191], v157 offset:36864
	ds_read_b128 v[192:195], v157 offset:37888
	ds_read_b128 v[196:199], v157 offset:38912
	ds_read_b128 v[200:203], v157 offset:39936
	global_load_lds_dwordx4 v[204:205], off
	v_lshl_add_u64 v[204:205], s[28:29], 0, v[132:133]
	s_mov_b32 m0, s40
	s_nop 0
	global_load_lds_dwordx4 v[204:205], off
	s_waitcnt lgkmcnt(8)
	s_barrier
	s_waitcnt lgkmcnt(0)
	s_setprio 1
	s_waitcnt lgkmcnt(0)
	v_mfma_f32_16x16x32_bf16 v[126:129], v[144:147], v[168:171], v[126:129]
	v_mfma_f32_16x16x32_bf16 v[122:125], v[160:163], v[168:171], v[122:125]
	v_mfma_f32_16x16x32_bf16 v[110:113], v[144:147], v[176:179], v[110:113]
	v_mfma_f32_16x16x32_bf16 v[106:109], v[160:163], v[176:179], v[106:109]
	v_mfma_f32_16x16x32_bf16 v[94:97], v[144:147], v[188:191], v[94:97]
	v_mfma_f32_16x16x32_bf16 v[90:93], v[160:163], v[188:191], v[90:93]
	v_mfma_f32_16x16x32_bf16 v[78:81], v[144:147], v[196:199], v[78:81]
	v_mfma_f32_16x16x32_bf16 v[74:77], v[160:163], v[196:199], v[74:77]
	v_mfma_f32_16x16x32_bf16 v[126:129], v[148:151], v[172:175], v[126:129]
	v_mfma_f32_16x16x32_bf16 v[122:125], v[164:167], v[172:175], v[122:125]
	v_mfma_f32_16x16x32_bf16 v[110:113], v[148:151], v[180:183], v[110:113]
	v_mfma_f32_16x16x32_bf16 v[106:109], v[164:167], v[180:183], v[106:109]
	v_mfma_f32_16x16x32_bf16 v[94:97], v[148:151], v[192:195], v[94:97]
	v_mfma_f32_16x16x32_bf16 v[90:93], v[164:167], v[192:195], v[90:93]
	v_mfma_f32_16x16x32_bf16 v[78:81], v[148:151], v[200:203], v[78:81]
	v_mfma_f32_16x16x32_bf16 v[74:77], v[164:167], v[200:203], v[74:77]
	s_setprio 0
	s_barrier
	s_add_i32 s28, 0, 0x1c000
	s_add_i32 s29, s57, s37
	v_add_u32_e32 v134, s28, v154
	v_lshl_add_u64 v[184:185], v[184:185], 0, s[10:11]
	s_mov_b32 m0, s29
	ds_read_b128 v[204:207], v134
	ds_read_b128 v[208:211], v134 offset:1024
	ds_read_b128 v[212:215], v134 offset:2048
	ds_read_b128 v[216:219], v134 offset:3072
	global_load_lds_dwordx4 v[184:185], off
	v_lshl_add_u64 v[184:185], v[220:221], 0, s[10:11]
	s_add_i32 m0, s29, 0x2000
	s_nop 0
	global_load_lds_dwordx4 v[184:185], off
	s_barrier
	s_waitcnt lgkmcnt(0)
	s_setprio 1
	s_waitcnt lgkmcnt(0)
	v_mfma_f32_16x16x32_bf16 v[118:121], v[204:207], v[168:171], v[118:121]
	v_mfma_f32_16x16x32_bf16 v[114:117], v[212:215], v[168:171], v[114:117]
	v_mfma_f32_16x16x32_bf16 v[102:105], v[204:207], v[176:179], v[102:105]
	v_mfma_f32_16x16x32_bf16 v[98:101], v[212:215], v[176:179], v[98:101]
	v_mfma_f32_16x16x32_bf16 v[86:89], v[204:207], v[188:191], v[86:89]
	v_mfma_f32_16x16x32_bf16 v[82:85], v[212:215], v[188:191], v[82:85]
	v_mfma_f32_16x16x32_bf16 v[70:73], v[204:207], v[196:199], v[70:73]
	v_mfma_f32_16x16x32_bf16 v[66:69], v[212:215], v[196:199], v[66:69]
	v_mfma_f32_16x16x32_bf16 v[118:121], v[208:211], v[172:175], v[118:121]
	v_mfma_f32_16x16x32_bf16 v[114:117], v[216:219], v[172:175], v[114:117]
	v_mfma_f32_16x16x32_bf16 v[102:105], v[208:211], v[180:183], v[102:105]
	v_mfma_f32_16x16x32_bf16 v[98:101], v[216:219], v[180:183], v[98:101]
	v_mfma_f32_16x16x32_bf16 v[86:89], v[208:211], v[192:195], v[86:89]
	v_mfma_f32_16x16x32_bf16 v[82:85], v[216:219], v[192:195], v[82:85]
	v_mfma_f32_16x16x32_bf16 v[70:73], v[208:211], v[200:203], v[70:73]
	v_mfma_f32_16x16x32_bf16 v[66:69], v[216:219], v[200:203], v[66:69]
	s_setprio 0
	s_mov_b32 m0, s44
	v_lshl_add_u64 v[184:185], v[222:223], 0, s[10:11]
	s_barrier
	ds_read_b128 v[168:171], v157 offset:49152
	ds_read_b128 v[172:175], v157 offset:50176
	ds_read_b128 v[176:179], v157 offset:51200
	ds_read_b128 v[180:183], v157 offset:52224
	ds_read_b128 v[188:191], v157 offset:53248
	ds_read_b128 v[192:195], v157 offset:54272
	ds_read_b128 v[196:199], v157 offset:55296
	ds_read_b128 v[200:203], v157 offset:56320
	global_load_lds_dwordx4 v[184:185], off
	v_lshl_add_u64 v[184:185], v[224:225], 0, s[10:11]
	s_mov_b32 m0, s45
	s_nop 0
	global_load_lds_dwordx4 v[184:185], off
	s_barrier
	s_waitcnt lgkmcnt(0)
	s_setprio 1
	s_waitcnt lgkmcnt(0)
	v_mfma_f32_16x16x32_bf16 v[62:65], v[144:147], v[168:171], v[62:65]
	v_mfma_f32_16x16x32_bf16 v[58:61], v[160:163], v[168:171], v[58:61]
	v_mfma_f32_16x16x32_bf16 v[46:49], v[144:147], v[176:179], v[46:49]
	v_mfma_f32_16x16x32_bf16 v[42:45], v[160:163], v[176:179], v[42:45]
	v_mfma_f32_16x16x32_bf16 v[30:33], v[144:147], v[188:191], v[30:33]
	v_mfma_f32_16x16x32_bf16 v[26:29], v[160:163], v[188:191], v[26:29]
	v_mfma_f32_16x16x32_bf16 v[14:17], v[144:147], v[196:199], v[14:17]
	v_mfma_f32_16x16x32_bf16 v[10:13], v[160:163], v[196:199], v[10:13]
	v_mfma_f32_16x16x32_bf16 v[62:65], v[148:151], v[172:175], v[62:65]
	v_mfma_f32_16x16x32_bf16 v[58:61], v[164:167], v[172:175], v[58:61]
	v_mfma_f32_16x16x32_bf16 v[46:49], v[148:151], v[180:183], v[46:49]
	v_mfma_f32_16x16x32_bf16 v[42:45], v[164:167], v[180:183], v[42:45]
	v_mfma_f32_16x16x32_bf16 v[30:33], v[148:151], v[192:195], v[30:33]
	v_mfma_f32_16x16x32_bf16 v[26:29], v[164:167], v[192:195], v[26:29]
	v_mfma_f32_16x16x32_bf16 v[14:17], v[148:151], v[200:203], v[14:17]
	v_mfma_f32_16x16x32_bf16 v[10:13], v[164:167], v[200:203], v[10:13]
	s_setprio 0
	s_barrier
	s_add_u32 s26, s26, 0x80080
	s_addc_u32 s27, s27, 0
	s_add_i32 s28, s28, s37
	v_lshl_add_u64 v[144:145], s[26:27], 0, v[130:131]
	s_mov_b32 m0, s28
	s_nop 0
	global_load_lds_dwordx4 v[144:145], off
	v_lshl_add_u64 v[144:145], s[26:27], 0, v[132:133]
	s_add_i32 m0, s28, 0x2000
	s_nop 0
	global_load_lds_dwordx4 v[144:145], off
	s_waitcnt vmcnt(6)
	s_barrier
	s_setprio 1
	v_mfma_f32_16x16x32_bf16 v[54:57], v[204:207], v[168:171], v[54:57]
	v_mfma_f32_16x16x32_bf16 v[50:53], v[212:215], v[168:171], v[50:53]
	v_mfma_f32_16x16x32_bf16 v[38:41], v[204:207], v[176:179], v[38:41]
	v_mfma_f32_16x16x32_bf16 v[34:37], v[212:215], v[176:179], v[34:37]
	v_mfma_f32_16x16x32_bf16 v[22:25], v[204:207], v[188:191], v[22:25]
	v_mfma_f32_16x16x32_bf16 v[18:21], v[212:215], v[188:191], v[18:21]
	v_mfma_f32_16x16x32_bf16 v[6:9], v[204:207], v[196:199], v[6:9]
	v_mfma_f32_16x16x32_bf16 v[2:5], v[212:215], v[196:199], v[2:5]
	v_mfma_f32_16x16x32_bf16 v[54:57], v[208:211], v[172:175], v[54:57]
	v_mfma_f32_16x16x32_bf16 v[50:53], v[216:219], v[172:175], v[50:53]
	v_mfma_f32_16x16x32_bf16 v[38:41], v[208:211], v[180:183], v[38:41]
	v_mfma_f32_16x16x32_bf16 v[34:37], v[216:219], v[180:183], v[34:37]
	v_mfma_f32_16x16x32_bf16 v[22:25], v[208:211], v[192:195], v[22:25]
	v_mfma_f32_16x16x32_bf16 v[18:21], v[216:219], v[192:195], v[18:21]
	v_mfma_f32_16x16x32_bf16 v[6:9], v[208:211], v[200:203], v[6:9]
	v_mfma_f32_16x16x32_bf16 v[2:5], v[216:219], v[200:203], v[2:5]
	s_setprio 0
	s_add_i32 s56, s56, 2
	s_add_u32 s24, s24, 0x100
	s_addc_u32 s25, s25, 0
	s_add_u32 s54, s54, 0x100
	s_addc_u32 s55, s55, 0
	s_cmp_gt_u32 s56, 29
	s_barrier
	s_cbranch_scc0 .LBB0_1662
	s_lshl_b32 s15, s2, 8
	s_add_i32 s15, s15, s43
	s_cmp_lt_u32 s2, 64
	v_or_b32_e32 v251, s15, v153
	s_cselect_b64 s[24:25], s[72:73], s[74:75]
	s_cselect_b32 s3, 0, 0x8000000
	s_sub_u32 s24, s24, s3
	s_subb_u32 s25, s25, 0
	s_add_u32 s26, s4, 0x4000
	s_addc_u32 s27, s5, 0
	v_cmp_gt_i32_e32 vcc, s42, v251
	v_lshl_or_b32 v249, s22, 8, v155
	v_lshlrev_b32_e32 v134, 13, v251
	v_lshlrev_b32_e32 v248, 12, v251
	v_lshl_add_u32 v134, v249, 2, v134
	v_lshl_add_u32 v248, v249, 1, v248
	v_lshlrev_b32_e32 v249, 2, v249
	v_bfe_u32 v252, v155, 2, 1
	v_mul_u32_u24_e32 v252, 24, v252
	v_add_u32_e32 v248, v248, v252
	v_add_u32_e32 v254, 0xffffc000, v251
	v_lshrrev_b32_e32 v255, 11, v251
	v_lshrrev_b32_e32 v254, 3, v254
	v_add_u32_e32 v254, 8, v254
	v_cndmask_b32_e32 v254, v254, v255, vcc
	v_mad_u32_u24 v254, v254, s50, v249
	global_load_dwordx4 v[188:191], v134, s[24:25]
	global_load_dwordx4 v[192:195], v134, s[24:25] offset:64
	global_load_dwordx4 v[196:199], v134, s[24:25] offset:512
	global_load_dwordx4 v[200:203], v134, s[24:25] offset:576
	global_load_dwordx4 v[204:207], v254, s[26:27]
	global_load_dwordx4 v[208:211], v254, s[26:27] offset:64
	global_load_dwordx4 v[212:215], v254, s[26:27] offset:512
	global_load_dwordx4 v[216:219], v254, s[26:27] offset:576
	v_add_u32_e32 v252, 0x20000, v134
	v_add_u32_e32 v255, 0x10, v251
	v_add_u32_e32 v254, 0xffffc010, v251
	v_lshrrev_b32_e32 v255, 11, v255
	v_lshrrev_b32_e32 v254, 3, v254
	v_add_u32_e32 v254, 8, v254
	v_cndmask_b32_e32 v254, v254, v255, vcc
	v_mad_u32_u24 v254, v254, s50, v249
	global_load_dwordx4 v[220:223], v252, s[24:25]
	global_load_dwordx4 v[224:227], v252, s[24:25] offset:64
	global_load_dwordx4 v[228:231], v252, s[24:25] offset:512
	global_load_dwordx4 v[232:235], v252, s[24:25] offset:576
	global_load_dwordx4 v[236:239], v254, s[26:27]
	global_load_dwordx4 v[240:243], v254, s[26:27] offset:64
	global_load_dwordx4 v[244:247], v254, s[26:27] offset:512
	global_load_dwordx4 v[144:147], v254, s[26:27] offset:576
	s_waitcnt vmcnt(8)
	v_pk_fma_f32 v[126:127], v[126:127], v[204:205], v[188:189]
	v_pk_fma_f32 v[128:129], v[128:129], v[206:207], v[190:191]
	v_pk_fma_f32 v[122:123], v[122:123], v[208:209], v[192:193]
	v_pk_fma_f32 v[124:125], v[124:125], v[210:211], v[194:195]
	v_pk_fma_f32 v[118:119], v[118:119], v[212:213], v[196:197]
	v_pk_fma_f32 v[120:121], v[120:121], v[214:215], v[198:199]
	v_pk_fma_f32 v[114:115], v[114:115], v[216:217], v[200:201]
	v_pk_fma_f32 v[116:117], v[116:117], v[218:219], v[202:203]
	v_cvt_pk_bf16_f32 v126, v126, v127
	v_cvt_pk_bf16_f32 v127, v128, v129
	v_cvt_pk_bf16_f32 v128, v122, v123
	v_cvt_pk_bf16_f32 v129, v124, v125
	v_cvt_pk_bf16_f32 v118, v118, v119
	v_cvt_pk_bf16_f32 v119, v120, v121
	v_cvt_pk_bf16_f32 v120, v114, v115
	v_cvt_pk_bf16_f32 v121, v116, v117
	v_permlane16_swap_b32_e32 v126, v128
	v_permlane16_swap_b32_e32 v127, v129
	v_permlane16_swap_b32_e32 v118, v120
	v_permlane16_swap_b32_e32 v119, v121
	global_store_dwordx4 v248, v[126:129], s[8:9]
	global_store_dwordx4 v248, v[118:121], s[8:9] offset:256
	v_add_u32_e32 v252, 0x40000, v134
	v_add_u32_e32 v255, 0x20, v251
	v_add_u32_e32 v254, 0xffffc020, v251
	v_lshrrev_b32_e32 v255, 11, v255
	v_lshrrev_b32_e32 v254, 3, v254
	v_add_u32_e32 v254, 8, v254
	v_cndmask_b32_e32 v254, v254, v255, vcc
	v_mad_u32_u24 v254, v254, s50, v249
	global_load_dwordx4 v[188:191], v252, s[24:25]
	global_load_dwordx4 v[192:195], v252, s[24:25] offset:64
	global_load_dwordx4 v[196:199], v252, s[24:25] offset:512
	global_load_dwordx4 v[200:203], v252, s[24:25] offset:576
	global_load_dwordx4 v[204:207], v254, s[26:27]
	global_load_dwordx4 v[208:211], v254, s[26:27] offset:64
	global_load_dwordx4 v[212:215], v254, s[26:27] offset:512
	global_load_dwordx4 v[216:219], v254, s[26:27] offset:576
	s_waitcnt vmcnt(10)
	v_pk_fma_f32 v[110:111], v[110:111], v[236:237], v[220:221]
	v_pk_fma_f32 v[112:113], v[112:113], v[238:239], v[222:223]
	v_pk_fma_f32 v[106:107], v[106:107], v[240:241], v[224:225]
	v_pk_fma_f32 v[108:109], v[108:109], v[242:243], v[226:227]
	v_pk_fma_f32 v[102:103], v[102:103], v[244:245], v[228:229]
	v_pk_fma_f32 v[104:105], v[104:105], v[246:247], v[230:231]
	v_pk_fma_f32 v[98:99], v[98:99], v[144:145], v[232:233]
	v_pk_fma_f32 v[100:101], v[100:101], v[146:147], v[234:235]
	v_add_u32_e32 v148, 0x10000, v248
	v_cvt_pk_bf16_f32 v110, v110, v111
	v_cvt_pk_bf16_f32 v111, v112, v113
	v_cvt_pk_bf16_f32 v112, v106, v107
	v_cvt_pk_bf16_f32 v113, v108, v109
	v_cvt_pk_bf16_f32 v102, v102, v103
	v_cvt_pk_bf16_f32 v103, v104, v105
	v_cvt_pk_bf16_f32 v104, v98, v99
	v_cvt_pk_bf16_f32 v105, v100, v101
	v_permlane16_swap_b32_e32 v110, v112
	v_permlane16_swap_b32_e32 v111, v113
	v_permlane16_swap_b32_e32 v102, v104
	v_permlane16_swap_b32_e32 v103, v105
	global_store_dwordx4 v148, v[110:113], s[8:9]
	global_store_dwordx4 v148, v[102:105], s[8:9] offset:256
	v_add_u32_e32 v252, 0x60000, v134
	v_add_u32_e32 v255, 0x30, v251
	v_add_u32_e32 v254, 0xffffc030, v251
	v_lshrrev_b32_e32 v255, 11, v255
	v_lshrrev_b32_e32 v254, 3, v254
	v_add_u32_e32 v254, 8, v254
	v_cndmask_b32_e32 v254, v254, v255, vcc
	v_mad_u32_u24 v254, v254, s50, v249
	global_load_dwordx4 v[220:223], v252, s[24:25]
	global_load_dwordx4 v[224:227], v252, s[24:25] offset:64
	global_load_dwordx4 v[228:231], v252, s[24:25] offset:512
	global_load_dwordx4 v[232:235], v252, s[24:25] offset:576
	global_load_dwordx4 v[236:239], v254, s[26:27]
	global_load_dwordx4 v[240:243], v254, s[26:27] offset:64
	global_load_dwordx4 v[244:247], v254, s[26:27] offset:512
	global_load_dwordx4 v[144:147], v254, s[26:27] offset:576
	s_waitcnt vmcnt(10)
	v_pk_fma_f32 v[94:95], v[94:95], v[204:205], v[188:189]
	v_pk_fma_f32 v[96:97], v[96:97], v[206:207], v[190:191]
	v_pk_fma_f32 v[90:91], v[90:91], v[208:209], v[192:193]
	v_pk_fma_f32 v[92:93], v[92:93], v[210:211], v[194:195]
	v_pk_fma_f32 v[86:87], v[86:87], v[212:213], v[196:197]
	v_pk_fma_f32 v[88:89], v[88:89], v[214:215], v[198:199]
	v_pk_fma_f32 v[82:83], v[82:83], v[216:217], v[200:201]
	v_pk_fma_f32 v[84:85], v[84:85], v[218:219], v[202:203]
	v_add_u32_e32 v148, 0x20000, v248
	v_cvt_pk_bf16_f32 v94, v94, v95
	v_cvt_pk_bf16_f32 v95, v96, v97
	v_cvt_pk_bf16_f32 v96, v90, v91
	v_cvt_pk_bf16_f32 v97, v92, v93
	v_cvt_pk_bf16_f32 v86, v86, v87
	v_cvt_pk_bf16_f32 v87, v88, v89
	v_cvt_pk_bf16_f32 v88, v82, v83
	v_cvt_pk_bf16_f32 v89, v84, v85
	v_permlane16_swap_b32_e32 v94, v96
	v_permlane16_swap_b32_e32 v95, v97
	v_permlane16_swap_b32_e32 v86, v88
	v_permlane16_swap_b32_e32 v87, v89
	global_store_dwordx4 v148, v[94:97], s[8:9]
	global_store_dwordx4 v148, v[86:89], s[8:9] offset:256
	v_add_u32_e32 v252, 0x100000, v134
	v_add_u32_e32 v255, 0x80, v251
	v_add_u32_e32 v254, 0xffffc080, v251
	v_lshrrev_b32_e32 v255, 11, v255
	v_lshrrev_b32_e32 v254, 3, v254
	v_add_u32_e32 v254, 8, v254
	v_cndmask_b32_e32 v254, v254, v255, vcc
	v_mad_u32_u24 v254, v254, s50, v249
	global_load_dwordx4 v[188:191], v252, s[24:25]
	global_load_dwordx4 v[192:195], v252, s[24:25] offset:64
	global_load_dwordx4 v[196:199], v252, s[24:25] offset:512
	global_load_dwordx4 v[200:203], v252, s[24:25] offset:576
	global_load_dwordx4 v[204:207], v254, s[26:27]
	global_load_dwordx4 v[208:211], v254, s[26:27] offset:64
	global_load_dwordx4 v[212:215], v254, s[26:27] offset:512
	global_load_dwordx4 v[216:219], v254, s[26:27] offset:576
	s_waitcnt vmcnt(10)
	v_pk_fma_f32 v[78:79], v[78:79], v[236:237], v[220:221]
	v_pk_fma_f32 v[80:81], v[80:81], v[238:239], v[222:223]
	v_pk_fma_f32 v[74:75], v[74:75], v[240:241], v[224:225]
	v_pk_fma_f32 v[76:77], v[76:77], v[242:243], v[226:227]
	v_pk_fma_f32 v[70:71], v[70:71], v[244:245], v[228:229]
	v_pk_fma_f32 v[72:73], v[72:73], v[246:247], v[230:231]
	v_pk_fma_f32 v[66:67], v[66:67], v[144:145], v[232:233]
	v_pk_fma_f32 v[68:69], v[68:69], v[146:147], v[234:235]
	v_add_u32_e32 v148, 0x30000, v248
	v_cvt_pk_bf16_f32 v78, v78, v79
	v_cvt_pk_bf16_f32 v79, v80, v81
	v_cvt_pk_bf16_f32 v80, v74, v75
	v_cvt_pk_bf16_f32 v81, v76, v77
	v_cvt_pk_bf16_f32 v70, v70, v71
	v_cvt_pk_bf16_f32 v71, v72, v73
	v_cvt_pk_bf16_f32 v72, v66, v67
	v_cvt_pk_bf16_f32 v73, v68, v69
	v_permlane16_swap_b32_e32 v78, v80
	v_permlane16_swap_b32_e32 v79, v81
	v_permlane16_swap_b32_e32 v70, v72
	v_permlane16_swap_b32_e32 v71, v73
	global_store_dwordx4 v148, v[78:81], s[8:9]
	global_store_dwordx4 v148, v[70:73], s[8:9] offset:256
	v_add_u32_e32 v252, 0x120000, v134
	v_add_u32_e32 v255, 0x90, v251
	v_add_u32_e32 v254, 0xffffc090, v251
	v_lshrrev_b32_e32 v255, 11, v255
	v_lshrrev_b32_e32 v254, 3, v254
	v_add_u32_e32 v254, 8, v254
	v_cndmask_b32_e32 v254, v254, v255, vcc
	v_mad_u32_u24 v254, v254, s50, v249
	global_load_dwordx4 v[220:223], v252, s[24:25]
	global_load_dwordx4 v[224:227], v252, s[24:25] offset:64
	global_load_dwordx4 v[228:231], v252, s[24:25] offset:512
	global_load_dwordx4 v[232:235], v252, s[24:25] offset:576
	global_load_dwordx4 v[236:239], v254, s[26:27]
	global_load_dwordx4 v[240:243], v254, s[26:27] offset:64
	global_load_dwordx4 v[244:247], v254, s[26:27] offset:512
	global_load_dwordx4 v[144:147], v254, s[26:27] offset:576
	s_waitcnt vmcnt(10)
	v_pk_fma_f32 v[62:63], v[62:63], v[204:205], v[188:189]
	v_pk_fma_f32 v[64:65], v[64:65], v[206:207], v[190:191]
	v_pk_fma_f32 v[58:59], v[58:59], v[208:209], v[192:193]
	v_pk_fma_f32 v[60:61], v[60:61], v[210:211], v[194:195]
	v_pk_fma_f32 v[54:55], v[54:55], v[212:213], v[196:197]
	v_pk_fma_f32 v[56:57], v[56:57], v[214:215], v[198:199]
	v_pk_fma_f32 v[50:51], v[50:51], v[216:217], v[200:201]
	v_pk_fma_f32 v[52:53], v[52:53], v[218:219], v[202:203]
	v_add_u32_e32 v148, 0x80000, v248
	v_cvt_pk_bf16_f32 v62, v62, v63
	v_cvt_pk_bf16_f32 v63, v64, v65
	v_cvt_pk_bf16_f32 v64, v58, v59
	v_cvt_pk_bf16_f32 v65, v60, v61
	v_cvt_pk_bf16_f32 v54, v54, v55
	v_cvt_pk_bf16_f32 v55, v56, v57
	v_cvt_pk_bf16_f32 v56, v50, v51
	v_cvt_pk_bf16_f32 v57, v52, v53
	v_permlane16_swap_b32_e32 v62, v64
	v_permlane16_swap_b32_e32 v63, v65
	v_permlane16_swap_b32_e32 v54, v56
	v_permlane16_swap_b32_e32 v55, v57
	global_store_dwordx4 v148, v[62:65], s[8:9]
	global_store_dwordx4 v148, v[54:57], s[8:9] offset:256
	v_add_u32_e32 v252, 0x140000, v134
	v_add_u32_e32 v255, 0xa0, v251
	v_add_u32_e32 v254, 0xffffc0a0, v251
	v_lshrrev_b32_e32 v255, 11, v255
	v_lshrrev_b32_e32 v254, 3, v254
	v_add_u32_e32 v254, 8, v254
	v_cndmask_b32_e32 v254, v254, v255, vcc
	v_mad_u32_u24 v254, v254, s50, v249
	global_load_dwordx4 v[188:191], v252, s[24:25]
	global_load_dwordx4 v[192:195], v252, s[24:25] offset:64
	global_load_dwordx4 v[196:199], v252, s[24:25] offset:512
	global_load_dwordx4 v[200:203], v252, s[24:25] offset:576
	global_load_dwordx4 v[204:207], v254, s[26:27]
	global_load_dwordx4 v[208:211], v254, s[26:27] offset:64
	global_load_dwordx4 v[212:215], v254, s[26:27] offset:512
	global_load_dwordx4 v[216:219], v254, s[26:27] offset:576
	s_waitcnt vmcnt(10)
	v_pk_fma_f32 v[46:47], v[46:47], v[236:237], v[220:221]
	v_pk_fma_f32 v[48:49], v[48:49], v[238:239], v[222:223]
	v_pk_fma_f32 v[42:43], v[42:43], v[240:241], v[224:225]
	v_pk_fma_f32 v[44:45], v[44:45], v[242:243], v[226:227]
	v_pk_fma_f32 v[38:39], v[38:39], v[244:245], v[228:229]
	v_pk_fma_f32 v[40:41], v[40:41], v[246:247], v[230:231]
	v_pk_fma_f32 v[34:35], v[34:35], v[144:145], v[232:233]
	v_pk_fma_f32 v[36:37], v[36:37], v[146:147], v[234:235]
	v_add_u32_e32 v148, 0x90000, v248
	v_cvt_pk_bf16_f32 v46, v46, v47
	v_cvt_pk_bf16_f32 v47, v48, v49
	v_cvt_pk_bf16_f32 v48, v42, v43
	v_cvt_pk_bf16_f32 v49, v44, v45
	v_cvt_pk_bf16_f32 v38, v38, v39
	v_cvt_pk_bf16_f32 v39, v40, v41
	v_cvt_pk_bf16_f32 v40, v34, v35
	v_cvt_pk_bf16_f32 v41, v36, v37
	v_permlane16_swap_b32_e32 v46, v48
	v_permlane16_swap_b32_e32 v47, v49
	v_permlane16_swap_b32_e32 v38, v40
	v_permlane16_swap_b32_e32 v39, v41
	global_store_dwordx4 v148, v[46:49], s[8:9]
	global_store_dwordx4 v148, v[38:41], s[8:9] offset:256
	v_add_u32_e32 v252, 0x160000, v134
	v_add_u32_e32 v255, 0xb0, v251
	v_add_u32_e32 v254, 0xffffc0b0, v251
	v_lshrrev_b32_e32 v255, 11, v255
	v_lshrrev_b32_e32 v254, 3, v254
	v_add_u32_e32 v254, 8, v254
	v_cndmask_b32_e32 v254, v254, v255, vcc
	v_mad_u32_u24 v254, v254, s50, v249
	global_load_dwordx4 v[220:223], v252, s[24:25]
	global_load_dwordx4 v[224:227], v252, s[24:25] offset:64
	global_load_dwordx4 v[228:231], v252, s[24:25] offset:512
	global_load_dwordx4 v[232:235], v252, s[24:25] offset:576
	global_load_dwordx4 v[236:239], v254, s[26:27]
	global_load_dwordx4 v[240:243], v254, s[26:27] offset:64
	global_load_dwordx4 v[244:247], v254, s[26:27] offset:512
	global_load_dwordx4 v[144:147], v254, s[26:27] offset:576
	s_waitcnt vmcnt(10)
	v_pk_fma_f32 v[30:31], v[30:31], v[204:205], v[188:189]
	v_pk_fma_f32 v[32:33], v[32:33], v[206:207], v[190:191]
	v_pk_fma_f32 v[26:27], v[26:27], v[208:209], v[192:193]
	v_pk_fma_f32 v[28:29], v[28:29], v[210:211], v[194:195]
	v_pk_fma_f32 v[22:23], v[22:23], v[212:213], v[196:197]
	v_pk_fma_f32 v[24:25], v[24:25], v[214:215], v[198:199]
	v_pk_fma_f32 v[18:19], v[18:19], v[216:217], v[200:201]
	v_pk_fma_f32 v[20:21], v[20:21], v[218:219], v[202:203]
	v_add_u32_e32 v148, 0xa0000, v248
	v_cvt_pk_bf16_f32 v30, v30, v31
	v_cvt_pk_bf16_f32 v31, v32, v33
	v_cvt_pk_bf16_f32 v32, v26, v27
	v_cvt_pk_bf16_f32 v33, v28, v29
	v_cvt_pk_bf16_f32 v22, v22, v23
	v_cvt_pk_bf16_f32 v23, v24, v25
	v_cvt_pk_bf16_f32 v24, v18, v19
	v_cvt_pk_bf16_f32 v25, v20, v21
	v_permlane16_swap_b32_e32 v30, v32
	v_permlane16_swap_b32_e32 v31, v33
	v_permlane16_swap_b32_e32 v22, v24
	v_permlane16_swap_b32_e32 v23, v25
	global_store_dwordx4 v148, v[30:33], s[8:9]
	global_store_dwordx4 v148, v[22:25], s[8:9] offset:256
	s_waitcnt vmcnt(2)
	v_pk_fma_f32 v[14:15], v[14:15], v[236:237], v[220:221]
	v_pk_fma_f32 v[16:17], v[16:17], v[238:239], v[222:223]
	v_pk_fma_f32 v[10:11], v[10:11], v[240:241], v[224:225]
	v_pk_fma_f32 v[12:13], v[12:13], v[242:243], v[226:227]
	v_pk_fma_f32 v[6:7], v[6:7], v[244:245], v[228:229]
	v_pk_fma_f32 v[8:9], v[8:9], v[246:247], v[230:231]
	v_pk_fma_f32 v[2:3], v[2:3], v[144:145], v[232:233]
	v_pk_fma_f32 v[4:5], v[4:5], v[146:147], v[234:235]
	v_add_u32_e32 v148, 0xb0000, v248
	v_cvt_pk_bf16_f32 v14, v14, v15
	v_cvt_pk_bf16_f32 v15, v16, v17
	v_cvt_pk_bf16_f32 v16, v10, v11
	v_cvt_pk_bf16_f32 v17, v12, v13
	v_cvt_pk_bf16_f32 v6, v6, v7
	v_cvt_pk_bf16_f32 v7, v8, v9
	v_cvt_pk_bf16_f32 v8, v2, v3
	v_cvt_pk_bf16_f32 v9, v4, v5
	v_permlane16_swap_b32_e32 v14, v16
	v_permlane16_swap_b32_e32 v15, v17
	v_permlane16_swap_b32_e32 v6, v8
	v_permlane16_swap_b32_e32 v7, v9
	global_store_dwordx4 v148, v[14:17], s[8:9]
	global_store_dwordx4 v148, v[6:9], s[8:9] offset:256
	s_and_b64 vcc, exec, s[0:1]
	s_mov_b32 s22, s14
	s_mov_b32 s2, s16
	s_mov_b64 s[26:27], s[20:21]
	s_mov_b64 s[24:25], s[18:19]
	s_cbranch_vccnz .LBB0_1695
	s_branch .LBB0_1659

.LBB0_1881:
	ds_read_b128 v[148:151], v144
	ds_read_b128 v[152:155], v144 offset:1024
	ds_read_b128 v[156:159], v144 offset:2048
	ds_read_b128 v[160:163], v144 offset:3072
	s_add_u32 s20, s18, 0xfff80080
	s_addc_u32 s21, s19, -1
	s_cmp_eq_u32 s48, 28
	s_cselect_b32 s23, s11, s21
	s_cselect_b32 s22, s44, s20
	s_cselect_b32 s21, s9, s47
	s_cselect_b32 s20, s45, s46
	v_lshl_add_u64 v[184:185], s[18:19], 0, v[134:135]
	s_add_i32 m0, s13, 0xc000
	ds_read_b128 v[164:167], v145
	ds_read_b128 v[168:171], v145 offset:1024
	ds_read_b128 v[172:175], v145 offset:2048
	ds_read_b128 v[176:179], v145 offset:3072
	ds_read_b128 v[180:183], v145 offset:4096
	ds_read_b128 v[188:191], v145 offset:5120
	ds_read_b128 v[192:195], v145 offset:6144
	ds_read_b128 v[196:199], v145 offset:7168
	global_load_lds_dwordx4 v[184:185], off
	v_lshl_add_u64 v[184:185], s[18:19], 0, v[136:137]
	s_add_i32 m0, s13, 0xe000
	s_nop 0
	global_load_lds_dwordx4 v[184:185], off
	s_waitcnt lgkmcnt(8)
	s_barrier
	s_waitcnt lgkmcnt(0)
	s_setprio 1
	s_waitcnt lgkmcnt(0)
	v_mfma_f32_16x16x32_bf16 v[126:129], v[148:151], v[164:167], v[126:129]
	v_mfma_f32_16x16x32_bf16 v[122:125], v[156:159], v[164:167], v[122:125]
	v_mfma_f32_16x16x32_bf16 v[118:121], v[148:151], v[172:175], v[118:121]
	v_mfma_f32_16x16x32_bf16 v[110:113], v[156:159], v[172:175], v[110:113]
	v_mfma_f32_16x16x32_bf16 v[102:105], v[148:151], v[180:183], v[102:105]
	v_mfma_f32_16x16x32_bf16 v[94:97], v[156:159], v[180:183], v[94:97]
	v_mfma_f32_16x16x32_bf16 v[86:89], v[148:151], v[192:195], v[86:89]
	v_mfma_f32_16x16x32_bf16 v[78:81], v[156:159], v[192:195], v[78:81]
	v_mfma_f32_16x16x32_bf16 v[126:129], v[152:155], v[168:171], v[126:129]
	v_mfma_f32_16x16x32_bf16 v[122:125], v[160:163], v[168:171], v[122:125]
	v_mfma_f32_16x16x32_bf16 v[118:121], v[152:155], v[176:179], v[118:121]
	v_mfma_f32_16x16x32_bf16 v[110:113], v[160:163], v[176:179], v[110:113]
	v_mfma_f32_16x16x32_bf16 v[102:105], v[152:155], v[188:191], v[102:105]
	v_mfma_f32_16x16x32_bf16 v[94:97], v[160:163], v[188:191], v[94:97]
	v_mfma_f32_16x16x32_bf16 v[86:89], v[152:155], v[196:199], v[86:89]
	v_mfma_f32_16x16x32_bf16 v[78:81], v[160:163], v[196:199], v[78:81]
	s_setprio 0
	s_barrier
	s_add_i32 s49, s41, s30
	v_lshl_add_u64 v[184:185], s[20:21], 0, v[132:133]
	s_mov_b32 m0, s49
	ds_read_b128 v[200:203], v146
	ds_read_b128 v[204:207], v146 offset:1024
	ds_read_b128 v[208:211], v146 offset:2048
	ds_read_b128 v[212:215], v146 offset:3072
	global_load_lds_dwordx4 v[184:185], off
	v_lshl_add_u64 v[216:217], s[20:21], 0, v[130:131]
	s_add_i32 m0, s49, 0x2000
	s_nop 0
	global_load_lds_dwordx4 v[216:217], off
	s_barrier
	s_waitcnt lgkmcnt(0)
	s_setprio 1
	s_waitcnt lgkmcnt(0)
	v_mfma_f32_16x16x32_bf16 v[114:117], v[200:203], v[164:167], v[114:117]
	v_mfma_f32_16x16x32_bf16 v[106:109], v[208:211], v[164:167], v[106:109]
	v_mfma_f32_16x16x32_bf16 v[98:101], v[200:203], v[172:175], v[98:101]
	v_mfma_f32_16x16x32_bf16 v[90:93], v[208:211], v[172:175], v[90:93]
	v_mfma_f32_16x16x32_bf16 v[82:85], v[200:203], v[180:183], v[82:85]
	v_mfma_f32_16x16x32_bf16 v[74:77], v[208:211], v[180:183], v[74:77]
	v_mfma_f32_16x16x32_bf16 v[70:73], v[200:203], v[192:195], v[70:73]
	v_mfma_f32_16x16x32_bf16 v[66:69], v[208:211], v[192:195], v[66:69]
	v_mfma_f32_16x16x32_bf16 v[114:117], v[204:207], v[168:171], v[114:117]
	v_mfma_f32_16x16x32_bf16 v[106:109], v[212:215], v[168:171], v[106:109]
	v_mfma_f32_16x16x32_bf16 v[98:101], v[204:207], v[176:179], v[98:101]
	v_mfma_f32_16x16x32_bf16 v[90:93], v[212:215], v[176:179], v[90:93]
	v_mfma_f32_16x16x32_bf16 v[82:85], v[204:207], v[188:191], v[82:85]
	v_mfma_f32_16x16x32_bf16 v[74:77], v[212:215], v[188:191], v[74:77]
	v_mfma_f32_16x16x32_bf16 v[70:73], v[204:207], v[196:199], v[70:73]
	v_mfma_f32_16x16x32_bf16 v[66:69], v[212:215], v[196:199], v[66:69]
	s_setprio 0
	s_mov_b32 m0, s13
	v_lshl_add_u64 v[218:219], s[22:23], 0, v[132:133]
	s_barrier
	ds_read_b128 v[164:167], v145 offset:16384
	ds_read_b128 v[168:171], v145 offset:17408
	ds_read_b128 v[172:175], v145 offset:18432
	ds_read_b128 v[176:179], v145 offset:19456
	ds_read_b128 v[180:183], v145 offset:20480
	ds_read_b128 v[188:191], v145 offset:21504
	ds_read_b128 v[192:195], v145 offset:22528
	ds_read_b128 v[196:199], v145 offset:23552
	global_load_lds_dwordx4 v[218:219], off
	v_lshl_add_u64 v[220:221], s[22:23], 0, v[130:131]
	s_mov_b32 m0, s34
	s_nop 0
	global_load_lds_dwordx4 v[220:221], off
	s_barrier
	s_waitcnt lgkmcnt(0)
	s_setprio 1
	s_waitcnt lgkmcnt(0)
	v_mfma_f32_16x16x32_bf16 v[62:65], v[148:151], v[164:167], v[62:65]
	v_mfma_f32_16x16x32_bf16 v[58:61], v[156:159], v[164:167], v[58:61]
	v_mfma_f32_16x16x32_bf16 v[54:57], v[148:151], v[172:175], v[54:57]
	v_mfma_f32_16x16x32_bf16 v[46:49], v[156:159], v[172:175], v[46:49]
	v_mfma_f32_16x16x32_bf16 v[38:41], v[148:151], v[180:183], v[38:41]
	v_mfma_f32_16x16x32_bf16 v[30:33], v[156:159], v[180:183], v[30:33]
	v_mfma_f32_16x16x32_bf16 v[22:25], v[148:151], v[192:195], v[22:25]
	v_mfma_f32_16x16x32_bf16 v[14:17], v[156:159], v[192:195], v[14:17]
	v_mfma_f32_16x16x32_bf16 v[62:65], v[152:155], v[168:171], v[62:65]
	v_mfma_f32_16x16x32_bf16 v[58:61], v[160:163], v[168:171], v[58:61]
	v_mfma_f32_16x16x32_bf16 v[54:57], v[152:155], v[176:179], v[54:57]
	v_mfma_f32_16x16x32_bf16 v[46:49], v[160:163], v[176:179], v[46:49]
	v_mfma_f32_16x16x32_bf16 v[38:41], v[152:155], v[188:191], v[38:41]
	v_mfma_f32_16x16x32_bf16 v[30:33], v[160:163], v[188:191], v[30:33]
	v_mfma_f32_16x16x32_bf16 v[22:25], v[152:155], v[196:199], v[22:25]
	v_mfma_f32_16x16x32_bf16 v[14:17], v[160:163], v[196:199], v[14:17]
	s_setprio 0
	s_barrier
	s_add_u32 s50, s20, 0x80000
	s_addc_u32 s51, s21, 0
	s_add_i32 s49, s42, s30
	v_lshl_add_u64 v[148:149], s[50:51], 0, v[132:133]
	s_mov_b32 m0, s49
	s_nop 0
	global_load_lds_dwordx4 v[148:149], off
	v_lshl_add_u64 v[148:149], s[50:51], 0, v[130:131]
	s_add_i32 m0, s49, 0x2000
	s_nop 0
	global_load_lds_dwordx4 v[148:149], off
	s_waitcnt vmcnt(6)
	s_barrier
	s_setprio 1
	v_mfma_f32_16x16x32_bf16 v[50:53], v[200:203], v[164:167], v[50:53]
	v_mfma_f32_16x16x32_bf16 v[42:45], v[208:211], v[164:167], v[42:45]
	v_mfma_f32_16x16x32_bf16 v[34:37], v[200:203], v[172:175], v[34:37]
	v_mfma_f32_16x16x32_bf16 v[26:29], v[208:211], v[172:175], v[26:29]
	v_mfma_f32_16x16x32_bf16 v[18:21], v[200:203], v[180:183], v[18:21]
	v_mfma_f32_16x16x32_bf16 v[10:13], v[208:211], v[180:183], v[10:13]
	v_mfma_f32_16x16x32_bf16 v[6:9], v[200:203], v[192:195], v[6:9]
	v_mfma_f32_16x16x32_bf16 v[2:5], v[208:211], v[192:195], v[2:5]
	v_mfma_f32_16x16x32_bf16 v[50:53], v[204:207], v[168:171], v[50:53]
	v_mfma_f32_16x16x32_bf16 v[42:45], v[212:215], v[168:171], v[42:45]
	v_mfma_f32_16x16x32_bf16 v[34:37], v[204:207], v[176:179], v[34:37]
	v_mfma_f32_16x16x32_bf16 v[26:29], v[212:215], v[176:179], v[26:29]
	v_mfma_f32_16x16x32_bf16 v[18:21], v[204:207], v[188:191], v[18:21]
	v_mfma_f32_16x16x32_bf16 v[10:13], v[212:215], v[188:191], v[10:13]
	v_mfma_f32_16x16x32_bf16 v[6:9], v[204:207], v[196:199], v[6:9]
	v_mfma_f32_16x16x32_bf16 v[2:5], v[212:215], v[196:199], v[2:5]
	s_setprio 0
	s_add_i32 s49, 0, 0x18000
	v_add_u32_e32 v147, s49, v142
	s_barrier
	ds_read_b128 v[148:151], v147
	ds_read_b128 v[152:155], v147 offset:1024
	ds_read_b128 v[156:159], v147 offset:2048
	ds_read_b128 v[160:163], v147 offset:3072
	s_add_u32 s22, s22, 0x80000
	s_addc_u32 s23, s23, 0
	s_mov_b32 m0, s35
	v_lshl_add_u64 v[200:201], s[22:23], 0, v[132:133]
	ds_read_b128 v[164:167], v145 offset:32768
	ds_read_b128 v[168:171], v145 offset:33792
	ds_read_b128 v[172:175], v145 offset:34816
	ds_read_b128 v[176:179], v145 offset:35840
	ds_read_b128 v[180:183], v145 offset:36864
	ds_read_b128 v[188:191], v145 offset:37888
	ds_read_b128 v[192:195], v145 offset:38912
	ds_read_b128 v[196:199], v145 offset:39936
	global_load_lds_dwordx4 v[200:201], off
	v_lshl_add_u64 v[200:201], s[22:23], 0, v[130:131]
	s_mov_b32 m0, s36
	s_nop 0
	global_load_lds_dwordx4 v[200:201], off
	s_waitcnt lgkmcnt(8)
	s_barrier
	s_waitcnt lgkmcnt(0)
	s_setprio 1
	s_waitcnt lgkmcnt(0)
	v_mfma_f32_16x16x32_bf16 v[126:129], v[148:151], v[164:167], v[126:129]
	v_mfma_f32_16x16x32_bf16 v[122:125], v[156:159], v[164:167], v[122:125]
	v_mfma_f32_16x16x32_bf16 v[118:121], v[148:151], v[172:175], v[118:121]
	v_mfma_f32_16x16x32_bf16 v[110:113], v[156:159], v[172:175], v[110:113]
	v_mfma_f32_16x16x32_bf16 v[102:105], v[148:151], v[180:183], v[102:105]
	v_mfma_f32_16x16x32_bf16 v[94:97], v[156:159], v[180:183], v[94:97]
	v_mfma_f32_16x16x32_bf16 v[86:89], v[148:151], v[192:195], v[86:89]
	v_mfma_f32_16x16x32_bf16 v[78:81], v[156:159], v[192:195], v[78:81]
	v_mfma_f32_16x16x32_bf16 v[126:129], v[152:155], v[168:171], v[126:129]
	v_mfma_f32_16x16x32_bf16 v[122:125], v[160:163], v[168:171], v[122:125]
	v_mfma_f32_16x16x32_bf16 v[118:121], v[152:155], v[176:179], v[118:121]
	v_mfma_f32_16x16x32_bf16 v[110:113], v[160:163], v[176:179], v[110:113]
	v_mfma_f32_16x16x32_bf16 v[102:105], v[152:155], v[188:191], v[102:105]
	v_mfma_f32_16x16x32_bf16 v[94:97], v[160:163], v[188:191], v[94:97]
	v_mfma_f32_16x16x32_bf16 v[86:89], v[152:155], v[196:199], v[86:89]
	v_mfma_f32_16x16x32_bf16 v[78:81], v[160:163], v[196:199], v[78:81]
	s_setprio 0
	s_barrier
	s_add_i32 s22, 0, 0x1c000
	s_add_i32 s23, s49, s30
	v_add_u32_e32 v147, s22, v142
	v_lshl_add_u64 v[184:185], v[184:185], 0, s[4:5]
	s_mov_b32 m0, s23
	ds_read_b128 v[200:203], v147
	ds_read_b128 v[204:207], v147 offset:1024
	ds_read_b128 v[208:211], v147 offset:2048
	ds_read_b128 v[212:215], v147 offset:3072
	global_load_lds_dwordx4 v[184:185], off
	v_lshl_add_u64 v[184:185], v[216:217], 0, s[4:5]
	s_add_i32 m0, s23, 0x2000
	s_nop 0
	global_load_lds_dwordx4 v[184:185], off
	s_barrier
	s_waitcnt lgkmcnt(0)
	s_setprio 1
	s_waitcnt lgkmcnt(0)
	v_mfma_f32_16x16x32_bf16 v[114:117], v[200:203], v[164:167], v[114:117]
	v_mfma_f32_16x16x32_bf16 v[106:109], v[208:211], v[164:167], v[106:109]
	v_mfma_f32_16x16x32_bf16 v[98:101], v[200:203], v[172:175], v[98:101]
	v_mfma_f32_16x16x32_bf16 v[90:93], v[208:211], v[172:175], v[90:93]
	v_mfma_f32_16x16x32_bf16 v[82:85], v[200:203], v[180:183], v[82:85]
	v_mfma_f32_16x16x32_bf16 v[74:77], v[208:211], v[180:183], v[74:77]
	v_mfma_f32_16x16x32_bf16 v[70:73], v[200:203], v[192:195], v[70:73]
	v_mfma_f32_16x16x32_bf16 v[66:69], v[208:211], v[192:195], v[66:69]
	v_mfma_f32_16x16x32_bf16 v[114:117], v[204:207], v[168:171], v[114:117]
	v_mfma_f32_16x16x32_bf16 v[106:109], v[212:215], v[168:171], v[106:109]
	v_mfma_f32_16x16x32_bf16 v[98:101], v[204:207], v[176:179], v[98:101]
	v_mfma_f32_16x16x32_bf16 v[90:93], v[212:215], v[176:179], v[90:93]
	v_mfma_f32_16x16x32_bf16 v[82:85], v[204:207], v[188:191], v[82:85]
	v_mfma_f32_16x16x32_bf16 v[74:77], v[212:215], v[188:191], v[74:77]
	v_mfma_f32_16x16x32_bf16 v[70:73], v[204:207], v[196:199], v[70:73]
	v_mfma_f32_16x16x32_bf16 v[66:69], v[212:215], v[196:199], v[66:69]
	s_setprio 0
	s_mov_b32 m0, s38
	v_lshl_add_u64 v[184:185], v[218:219], 0, s[4:5]
	s_barrier
	ds_read_b128 v[164:167], v145 offset:49152
	ds_read_b128 v[168:171], v145 offset:50176
	ds_read_b128 v[172:175], v145 offset:51200
	ds_read_b128 v[176:179], v145 offset:52224
	ds_read_b128 v[180:183], v145 offset:53248
	ds_read_b128 v[188:191], v145 offset:54272
	ds_read_b128 v[192:195], v145 offset:55296
	ds_read_b128 v[196:199], v145 offset:56320
	global_load_lds_dwordx4 v[184:185], off
	v_lshl_add_u64 v[184:185], v[220:221], 0, s[4:5]
	s_mov_b32 m0, s39
	s_nop 0
	global_load_lds_dwordx4 v[184:185], off
	s_barrier
	s_waitcnt lgkmcnt(0)
	s_setprio 1
	s_waitcnt lgkmcnt(0)
	v_mfma_f32_16x16x32_bf16 v[62:65], v[148:151], v[164:167], v[62:65]
	v_mfma_f32_16x16x32_bf16 v[58:61], v[156:159], v[164:167], v[58:61]
	v_mfma_f32_16x16x32_bf16 v[54:57], v[148:151], v[172:175], v[54:57]
	v_mfma_f32_16x16x32_bf16 v[46:49], v[156:159], v[172:175], v[46:49]
	v_mfma_f32_16x16x32_bf16 v[38:41], v[148:151], v[180:183], v[38:41]
	v_mfma_f32_16x16x32_bf16 v[30:33], v[156:159], v[180:183], v[30:33]
	v_mfma_f32_16x16x32_bf16 v[22:25], v[148:151], v[192:195], v[22:25]
	v_mfma_f32_16x16x32_bf16 v[14:17], v[156:159], v[192:195], v[14:17]
	v_mfma_f32_16x16x32_bf16 v[62:65], v[152:155], v[168:171], v[62:65]
	v_mfma_f32_16x16x32_bf16 v[58:61], v[160:163], v[168:171], v[58:61]
	v_mfma_f32_16x16x32_bf16 v[54:57], v[152:155], v[176:179], v[54:57]
	v_mfma_f32_16x16x32_bf16 v[46:49], v[160:163], v[176:179], v[46:49]
	v_mfma_f32_16x16x32_bf16 v[38:41], v[152:155], v[188:191], v[38:41]
	v_mfma_f32_16x16x32_bf16 v[30:33], v[160:163], v[188:191], v[30:33]
	v_mfma_f32_16x16x32_bf16 v[22:25], v[152:155], v[196:199], v[22:25]
	v_mfma_f32_16x16x32_bf16 v[14:17], v[160:163], v[196:199], v[14:17]
	s_setprio 0
	s_barrier
	s_add_u32 s20, s20, 0x80080
	s_addc_u32 s21, s21, 0
	s_add_i32 s22, s22, s30
	v_lshl_add_u64 v[148:149], s[20:21], 0, v[132:133]
	s_mov_b32 m0, s22
	s_nop 0
	global_load_lds_dwordx4 v[148:149], off
	v_lshl_add_u64 v[148:149], s[20:21], 0, v[130:131]
	s_add_i32 m0, s22, 0x2000
	s_nop 0
	global_load_lds_dwordx4 v[148:149], off
	s_waitcnt vmcnt(6)
	s_barrier
	s_setprio 1
	v_mfma_f32_16x16x32_bf16 v[50:53], v[200:203], v[164:167], v[50:53]
	v_mfma_f32_16x16x32_bf16 v[42:45], v[208:211], v[164:167], v[42:45]
	v_mfma_f32_16x16x32_bf16 v[34:37], v[200:203], v[172:175], v[34:37]
	v_mfma_f32_16x16x32_bf16 v[26:29], v[208:211], v[172:175], v[26:29]
	v_mfma_f32_16x16x32_bf16 v[18:21], v[200:203], v[180:183], v[18:21]
	v_mfma_f32_16x16x32_bf16 v[10:13], v[208:211], v[180:183], v[10:13]
	v_mfma_f32_16x16x32_bf16 v[6:9], v[200:203], v[192:195], v[6:9]
	v_mfma_f32_16x16x32_bf16 v[2:5], v[208:211], v[192:195], v[2:5]
	v_mfma_f32_16x16x32_bf16 v[50:53], v[204:207], v[168:171], v[50:53]
	v_mfma_f32_16x16x32_bf16 v[42:45], v[212:215], v[168:171], v[42:45]
	v_mfma_f32_16x16x32_bf16 v[34:37], v[204:207], v[176:179], v[34:37]
	v_mfma_f32_16x16x32_bf16 v[26:29], v[212:215], v[176:179], v[26:29]
	v_mfma_f32_16x16x32_bf16 v[18:21], v[204:207], v[188:191], v[18:21]
	v_mfma_f32_16x16x32_bf16 v[10:13], v[212:215], v[188:191], v[10:13]
	v_mfma_f32_16x16x32_bf16 v[6:9], v[204:207], v[196:199], v[6:9]
	v_mfma_f32_16x16x32_bf16 v[2:5], v[212:215], v[196:199], v[2:5]
	s_setprio 0
	s_add_i32 s48, s48, 2
	s_add_u32 s18, s18, 0x100
	s_addc_u32 s19, s19, 0
	s_add_u32 s46, s46, 0x100
	s_addc_u32 s47, s47, 0
	s_cmp_gt_u32 s48, 29
	s_barrier
	s_cbranch_scc0 .LBB0_1881
	v_lshl_add_u32 v150, s12, 8, v1
	v_lshl_or_b32 v148, s43, 8, v143
	v_bfe_u32 v149, v143, 2, 1
	v_lshlrev_b32_e32 v150, 12, v150
	v_mul_u32_u24_e32 v149, 24, v149
	v_lshl_add_u32 v150, v148, 1, v150
	v_add_u32_e32 v150, v150, v149
	v_cvt_pk_bf16_f32 v126, v126, v127
	v_cvt_pk_bf16_f32 v127, v128, v129
	v_cvt_pk_bf16_f32 v128, v122, v123
	v_cvt_pk_bf16_f32 v129, v124, v125
	v_cvt_pk_bf16_f32 v114, v114, v115
	v_cvt_pk_bf16_f32 v115, v116, v117
	v_cvt_pk_bf16_f32 v116, v106, v107
	v_cvt_pk_bf16_f32 v117, v108, v109
	v_permlane16_swap_b32_e32 v126, v128
	v_permlane16_swap_b32_e32 v127, v129
	v_permlane16_swap_b32_e32 v114, v116
	v_permlane16_swap_b32_e32 v115, v117
	global_store_dwordx4 v150, v[126:129], s[2:3]
	global_store_dwordx4 v150, v[114:117], s[2:3] offset:256
	v_cvt_pk_bf16_f32 v118, v118, v119
	v_cvt_pk_bf16_f32 v119, v120, v121
	v_cvt_pk_bf16_f32 v120, v110, v111
	v_cvt_pk_bf16_f32 v121, v112, v113
	v_cvt_pk_bf16_f32 v98, v98, v99
	v_cvt_pk_bf16_f32 v99, v100, v101
	v_cvt_pk_bf16_f32 v100, v90, v91
	v_cvt_pk_bf16_f32 v101, v92, v93
	v_add_u32_e32 v151, 0x10000, v150
	v_permlane16_swap_b32_e32 v118, v120
	v_permlane16_swap_b32_e32 v119, v121
	v_permlane16_swap_b32_e32 v98, v100
	v_permlane16_swap_b32_e32 v99, v101
	global_store_dwordx4 v151, v[118:121], s[2:3]
	global_store_dwordx4 v151, v[98:101], s[2:3] offset:256
	v_cvt_pk_bf16_f32 v102, v102, v103
	v_cvt_pk_bf16_f32 v103, v104, v105
	v_cvt_pk_bf16_f32 v104, v94, v95
	v_cvt_pk_bf16_f32 v105, v96, v97
	v_cvt_pk_bf16_f32 v82, v82, v83
	v_cvt_pk_bf16_f32 v83, v84, v85
	v_cvt_pk_bf16_f32 v84, v74, v75
	v_cvt_pk_bf16_f32 v85, v76, v77
	v_add_u32_e32 v151, 0x20000, v150
	v_permlane16_swap_b32_e32 v102, v104
	v_permlane16_swap_b32_e32 v103, v105
	v_permlane16_swap_b32_e32 v82, v84
	v_permlane16_swap_b32_e32 v83, v85
	global_store_dwordx4 v151, v[102:105], s[2:3]
	global_store_dwordx4 v151, v[82:85], s[2:3] offset:256
	v_cvt_pk_bf16_f32 v86, v86, v87
	v_cvt_pk_bf16_f32 v87, v88, v89
	v_cvt_pk_bf16_f32 v88, v78, v79
	v_cvt_pk_bf16_f32 v89, v80, v81
	v_cvt_pk_bf16_f32 v70, v70, v71
	v_cvt_pk_bf16_f32 v71, v72, v73
	v_cvt_pk_bf16_f32 v72, v66, v67
	v_cvt_pk_bf16_f32 v73, v68, v69
	v_add_u32_e32 v151, 0x30000, v150
	v_permlane16_swap_b32_e32 v86, v88
	v_permlane16_swap_b32_e32 v87, v89
	v_permlane16_swap_b32_e32 v70, v72
	v_permlane16_swap_b32_e32 v71, v73
	global_store_dwordx4 v151, v[86:89], s[2:3]
	global_store_dwordx4 v151, v[70:73], s[2:3] offset:256
	v_cvt_pk_bf16_f32 v62, v62, v63
	v_cvt_pk_bf16_f32 v63, v64, v65
	v_cvt_pk_bf16_f32 v64, v58, v59
	v_cvt_pk_bf16_f32 v65, v60, v61
	v_cvt_pk_bf16_f32 v50, v50, v51
	v_cvt_pk_bf16_f32 v51, v52, v53
	v_cvt_pk_bf16_f32 v52, v42, v43
	v_cvt_pk_bf16_f32 v53, v44, v45
	v_add_u32_e32 v151, 0x80000, v150
	v_permlane16_swap_b32_e32 v62, v64
	v_permlane16_swap_b32_e32 v63, v65
	v_permlane16_swap_b32_e32 v50, v52
	v_permlane16_swap_b32_e32 v51, v53
	global_store_dwordx4 v151, v[62:65], s[2:3]
	global_store_dwordx4 v151, v[50:53], s[2:3] offset:256
	v_cvt_pk_bf16_f32 v54, v54, v55
	v_cvt_pk_bf16_f32 v55, v56, v57
	v_cvt_pk_bf16_f32 v56, v46, v47
	v_cvt_pk_bf16_f32 v57, v48, v49
	v_cvt_pk_bf16_f32 v34, v34, v35
	v_cvt_pk_bf16_f32 v35, v36, v37
	v_cvt_pk_bf16_f32 v36, v26, v27
	v_cvt_pk_bf16_f32 v37, v28, v29
	v_add_u32_e32 v151, 0x90000, v150
	v_permlane16_swap_b32_e32 v54, v56
	v_permlane16_swap_b32_e32 v55, v57
	v_permlane16_swap_b32_e32 v34, v36
	v_permlane16_swap_b32_e32 v35, v37
	global_store_dwordx4 v151, v[54:57], s[2:3]
	global_store_dwordx4 v151, v[34:37], s[2:3] offset:256
	v_cvt_pk_bf16_f32 v38, v38, v39
	v_cvt_pk_bf16_f32 v39, v40, v41
	v_cvt_pk_bf16_f32 v40, v30, v31
	v_cvt_pk_bf16_f32 v41, v32, v33
	v_cvt_pk_bf16_f32 v18, v18, v19
	v_cvt_pk_bf16_f32 v19, v20, v21
	v_cvt_pk_bf16_f32 v20, v10, v11
	v_cvt_pk_bf16_f32 v21, v12, v13
	v_add_u32_e32 v151, 0xa0000, v150
	v_permlane16_swap_b32_e32 v38, v40
	v_permlane16_swap_b32_e32 v39, v41
	v_permlane16_swap_b32_e32 v18, v20
	v_permlane16_swap_b32_e32 v19, v21
	global_store_dwordx4 v151, v[38:41], s[2:3]
	global_store_dwordx4 v151, v[18:21], s[2:3] offset:256
	v_cvt_pk_bf16_f32 v22, v22, v23
	v_cvt_pk_bf16_f32 v23, v24, v25
	v_cvt_pk_bf16_f32 v24, v14, v15
	v_cvt_pk_bf16_f32 v25, v16, v17
	v_cvt_pk_bf16_f32 v6, v6, v7
	v_cvt_pk_bf16_f32 v7, v8, v9
	v_cvt_pk_bf16_f32 v8, v2, v3
	v_cvt_pk_bf16_f32 v9, v4, v5
	v_add_u32_e32 v151, 0xb0000, v150
	v_permlane16_swap_b32_e32 v22, v24
	v_permlane16_swap_b32_e32 v23, v25
	v_permlane16_swap_b32_e32 v6, v8
	v_permlane16_swap_b32_e32 v7, v9
	global_store_dwordx4 v151, v[22:25], s[2:3]
	global_store_dwordx4 v151, v[6:9], s[2:3] offset:256
	s_and_b64 vcc, exec, s[0:1]
	s_mov_b32 s43, s8
	s_mov_b32 s12, s10
	s_mov_b64 s[20:21], s[16:17]
	s_mov_b64 s[18:19], s[14:15]
	s_cbranch_vccz .LBB0_1878
	s_waitcnt vmcnt(0)
	s_cmpk_gt_u32 s25, 0xff
	s_cbranch_scc1 .LBB0_1885
	s_barrier
